# GEMM compute blocks: single lgkmcnt(0) before 32 MFMAs replaced by counted lgkmcnt waits so MFMAs start after their own fragments land (on top of mod_unit loop rewrite)
# baseline (speedup 1.0000x reference)
.LBB0_131:
	s_and_b32 s14, s16, 0x8000
	v_add_u32_e32 v122, s14, v88
	v_or_b32_e32 v138, s14, v89
	v_add_u32_e32 v102, v122, v86
	v_add_u32_e32 v118, v138, v86
	v_add_u32_e32 v134, v122, v87
	v_add_u32_e32 v146, v138, v87
	ds_read_b128 v[90:93], v102
	ds_read_b128 v[94:97], v102 offset:2048
	ds_read_b128 v[98:101], v102 offset:4096
	ds_read_b128 v[102:105], v102 offset:6144
	ds_read_b128 v[106:109], v118 offset:16384
	ds_read_b128 v[110:113], v118 offset:18432
	ds_read_b128 v[114:117], v118 offset:20480
	ds_read_b128 v[118:121], v118 offset:22528
	ds_read_b128 v[122:125], v134
	ds_read_b128 v[126:129], v134 offset:2048
	ds_read_b128 v[130:133], v134 offset:4096
	ds_read_b128 v[134:137], v134 offset:6144
	ds_read_b128 v[138:141], v146 offset:16384
	ds_read_b128 v[142:145], v146 offset:18432
	ds_read_b128 v[150:153], v146 offset:20480
	ds_read_b128 v[154:157], v146 offset:22528
	s_waitcnt lgkmcnt(11)
	v_mfma_f32_16x16x32_bf16 v[52:55], v[90:93], v[106:109], v[52:55]
	s_add_i32 s16, s16, 0x8000
	s_add_u32 s28, s28, 0x80
	s_addc_u32 s29, s29, 0
	s_waitcnt lgkmcnt(10)
	v_mfma_f32_16x16x32_bf16 v[48:51], v[90:93], v[110:113], v[48:51]
	s_add_i32 s17, s17, 1
	s_cmpk_lg_i32 s28, 0x2000
	s_waitcnt lgkmcnt(9)
	v_mfma_f32_16x16x32_bf16 v[44:47], v[90:93], v[114:117], v[44:47]
	s_waitcnt lgkmcnt(8)
	v_mfma_f32_16x16x32_bf16 v[40:43], v[90:93], v[118:121], v[40:43]
	v_mfma_f32_16x16x32_bf16 v[36:39], v[94:97], v[106:109], v[36:39]
	v_mfma_f32_16x16x32_bf16 v[32:35], v[94:97], v[110:113], v[32:35]
	v_mfma_f32_16x16x32_bf16 v[28:31], v[94:97], v[114:117], v[28:31]
	v_mfma_f32_16x16x32_bf16 v[24:27], v[94:97], v[118:121], v[24:27]
	v_mfma_f32_16x16x32_bf16 v[20:23], v[98:101], v[106:109], v[20:23]
	v_mfma_f32_16x16x32_bf16 v[16:19], v[98:101], v[110:113], v[16:19]
	v_mfma_f32_16x16x32_bf16 v[12:15], v[98:101], v[114:117], v[12:15]
	v_mfma_f32_16x16x32_bf16 v[8:11], v[98:101], v[118:121], v[8:11]
	v_mfma_f32_16x16x32_bf16 v[4:7], v[102:105], v[106:109], v[4:7]
	v_mfma_f32_16x16x32_bf16 v[0:3], v[102:105], v[110:113], v[0:3]
	v_mfma_f32_16x16x32_bf16 v[56:59], v[102:105], v[114:117], v[56:59]
	v_mfma_f32_16x16x32_bf16 v[60:63], v[102:105], v[118:121], v[60:63]
	s_waitcnt lgkmcnt(3)
	v_mfma_f32_16x16x32_bf16 v[52:55], v[122:125], v[138:141], v[52:55]
	s_waitcnt lgkmcnt(2)
	v_mfma_f32_16x16x32_bf16 v[48:51], v[122:125], v[142:145], v[48:51]
	s_waitcnt lgkmcnt(1)
	v_mfma_f32_16x16x32_bf16 v[44:47], v[122:125], v[150:153], v[44:47]
	s_waitcnt lgkmcnt(0)
	v_mfma_f32_16x16x32_bf16 v[40:43], v[122:125], v[154:157], v[40:43]
	v_mfma_f32_16x16x32_bf16 v[36:39], v[126:129], v[138:141], v[36:39]
	v_mfma_f32_16x16x32_bf16 v[32:35], v[126:129], v[142:145], v[32:35]
	v_mfma_f32_16x16x32_bf16 v[28:31], v[126:129], v[150:153], v[28:31]
	v_mfma_f32_16x16x32_bf16 v[24:27], v[126:129], v[154:157], v[24:27]
	v_mfma_f32_16x16x32_bf16 v[20:23], v[130:133], v[138:141], v[20:23]
	v_mfma_f32_16x16x32_bf16 v[16:19], v[130:133], v[142:145], v[16:19]
	v_mfma_f32_16x16x32_bf16 v[12:15], v[130:133], v[150:153], v[12:15]
	v_mfma_f32_16x16x32_bf16 v[8:11], v[130:133], v[154:157], v[8:11]
	v_mfma_f32_16x16x32_bf16 v[4:7], v[134:137], v[138:141], v[4:7]
	v_mfma_f32_16x16x32_bf16 v[0:3], v[134:137], v[142:145], v[0:3]
	v_mfma_f32_16x16x32_bf16 v[56:59], v[134:137], v[150:153], v[56:59]
	v_mfma_f32_16x16x32_bf16 v[60:63], v[134:137], v[154:157], v[60:63]
	s_cbranch_scc0 .LBB0_138

.LBB0_192:
	s_and_b32 s14, s16, 0x8000
	v_add_u32_e32 v122, s14, v88
	v_or_b32_e32 v138, s14, v89
	v_add_u32_e32 v102, v122, v86
	v_add_u32_e32 v118, v138, v86
	v_add_u32_e32 v134, v122, v87
	v_add_u32_e32 v146, v138, v87
	ds_read_b128 v[90:93], v102
	ds_read_b128 v[94:97], v102 offset:2048
	ds_read_b128 v[98:101], v102 offset:4096
	ds_read_b128 v[102:105], v102 offset:6144
	ds_read_b128 v[106:109], v118 offset:16384
	ds_read_b128 v[110:113], v118 offset:18432
	ds_read_b128 v[114:117], v118 offset:20480
	ds_read_b128 v[118:121], v118 offset:22528
	ds_read_b128 v[122:125], v134
	ds_read_b128 v[126:129], v134 offset:2048
	ds_read_b128 v[130:133], v134 offset:4096
	ds_read_b128 v[134:137], v134 offset:6144
	ds_read_b128 v[138:141], v146 offset:16384
	ds_read_b128 v[142:145], v146 offset:18432
	ds_read_b128 v[150:153], v146 offset:20480
	ds_read_b128 v[154:157], v146 offset:22528
	s_waitcnt lgkmcnt(11)
	v_mfma_f32_16x16x32_bf16 v[60:63], v[90:93], v[106:109], v[60:63]
	s_add_i32 s16, s16, 0x8000
	s_add_u32 s22, s22, 0x80
	s_addc_u32 s23, s23, 0
	s_waitcnt lgkmcnt(10)
	v_mfma_f32_16x16x32_bf16 v[56:59], v[90:93], v[110:113], v[56:59]
	s_add_i32 s17, s17, 1
	s_cmpk_lg_i32 s22, 0x800
	s_waitcnt lgkmcnt(9)
	v_mfma_f32_16x16x32_bf16 v[52:55], v[90:93], v[114:117], v[52:55]
	s_waitcnt lgkmcnt(8)
	v_mfma_f32_16x16x32_bf16 v[48:51], v[90:93], v[118:121], v[48:51]
	v_mfma_f32_16x16x32_bf16 v[44:47], v[94:97], v[106:109], v[44:47]
	v_mfma_f32_16x16x32_bf16 v[40:43], v[94:97], v[110:113], v[40:43]
	v_mfma_f32_16x16x32_bf16 v[36:39], v[94:97], v[114:117], v[36:39]
	v_mfma_f32_16x16x32_bf16 v[32:35], v[94:97], v[118:121], v[32:35]
	v_mfma_f32_16x16x32_bf16 v[28:31], v[98:101], v[106:109], v[28:31]
	v_mfma_f32_16x16x32_bf16 v[24:27], v[98:101], v[110:113], v[24:27]
	v_mfma_f32_16x16x32_bf16 v[20:23], v[98:101], v[114:117], v[20:23]
	v_mfma_f32_16x16x32_bf16 v[16:19], v[98:101], v[118:121], v[16:19]
	v_mfma_f32_16x16x32_bf16 v[8:11], v[102:105], v[106:109], v[8:11]
	v_mfma_f32_16x16x32_bf16 v[0:3], v[102:105], v[110:113], v[0:3]
	v_mfma_f32_16x16x32_bf16 v[12:15], v[102:105], v[114:117], v[12:15]
	v_mfma_f32_16x16x32_bf16 v[4:7], v[102:105], v[118:121], v[4:7]
	s_waitcnt lgkmcnt(3)
	v_mfma_f32_16x16x32_bf16 v[60:63], v[122:125], v[138:141], v[60:63]
	s_waitcnt lgkmcnt(2)
	v_mfma_f32_16x16x32_bf16 v[56:59], v[122:125], v[142:145], v[56:59]
	s_waitcnt lgkmcnt(1)
	v_mfma_f32_16x16x32_bf16 v[52:55], v[122:125], v[150:153], v[52:55]
	s_waitcnt lgkmcnt(0)
	v_mfma_f32_16x16x32_bf16 v[48:51], v[122:125], v[154:157], v[48:51]
	v_mfma_f32_16x16x32_bf16 v[44:47], v[126:129], v[138:141], v[44:47]
	v_mfma_f32_16x16x32_bf16 v[40:43], v[126:129], v[142:145], v[40:43]
	v_mfma_f32_16x16x32_bf16 v[36:39], v[126:129], v[150:153], v[36:39]
	v_mfma_f32_16x16x32_bf16 v[32:35], v[126:129], v[154:157], v[32:35]
	v_mfma_f32_16x16x32_bf16 v[28:31], v[130:133], v[138:141], v[28:31]
	v_mfma_f32_16x16x32_bf16 v[24:27], v[130:133], v[142:145], v[24:27]
	v_mfma_f32_16x16x32_bf16 v[20:23], v[130:133], v[150:153], v[20:23]
	v_mfma_f32_16x16x32_bf16 v[16:19], v[130:133], v[154:157], v[16:19]
	v_mfma_f32_16x16x32_bf16 v[8:11], v[134:137], v[138:141], v[8:11]
	v_mfma_f32_16x16x32_bf16 v[0:3], v[134:137], v[142:145], v[0:3]
	v_mfma_f32_16x16x32_bf16 v[12:15], v[134:137], v[150:153], v[12:15]
	v_mfma_f32_16x16x32_bf16 v[4:7], v[134:137], v[154:157], v[4:7]
	s_cbranch_scc0 .LBB0_177

.LBB0_264:
	s_and_b32 s14, s16, 0x8000
	v_add_u32_e32 v122, s14, v87
	v_or_b32_e32 v138, s14, v89
	v_add_u32_e32 v102, v122, v85
	v_add_u32_e32 v118, v138, v85
	v_add_u32_e32 v134, v122, v86
	v_add_u32_e32 v146, v138, v86
	ds_read_b128 v[90:93], v102
	ds_read_b128 v[94:97], v102 offset:2048
	ds_read_b128 v[98:101], v102 offset:4096
	ds_read_b128 v[102:105], v102 offset:6144
	ds_read_b128 v[106:109], v118 offset:16384
	ds_read_b128 v[110:113], v118 offset:18432
	ds_read_b128 v[114:117], v118 offset:20480
	ds_read_b128 v[118:121], v118 offset:22528
	ds_read_b128 v[122:125], v134
	ds_read_b128 v[126:129], v134 offset:2048
	ds_read_b128 v[130:133], v134 offset:4096
	ds_read_b128 v[134:137], v134 offset:6144
	ds_read_b128 v[138:141], v146 offset:16384
	ds_read_b128 v[142:145], v146 offset:18432
	ds_read_b128 v[150:153], v146 offset:20480
	ds_read_b128 v[154:157], v146 offset:22528
	s_waitcnt lgkmcnt(11)
	v_mfma_f32_16x16x32_bf16 v[44:47], v[90:93], v[106:109], v[44:47]
	s_add_i32 s16, s16, 0x8000
	s_add_u32 s40, s40, 0x80
	s_addc_u32 s41, s41, 0
	s_waitcnt lgkmcnt(10)
	v_mfma_f32_16x16x32_bf16 v[40:43], v[90:93], v[110:113], v[40:43]
	s_add_i32 s17, s17, 1
	s_cmpk_lg_i32 s40, 0x800
	s_waitcnt lgkmcnt(9)
	v_mfma_f32_16x16x32_bf16 v[36:39], v[90:93], v[114:117], v[36:39]
	s_waitcnt lgkmcnt(8)
	v_mfma_f32_16x16x32_bf16 v[32:35], v[90:93], v[118:121], v[32:35]
	v_mfma_f32_16x16x32_bf16 v[28:31], v[94:97], v[106:109], v[28:31]
	v_mfma_f32_16x16x32_bf16 v[24:27], v[94:97], v[110:113], v[24:27]
	v_mfma_f32_16x16x32_bf16 v[20:23], v[94:97], v[114:117], v[20:23]
	v_mfma_f32_16x16x32_bf16 v[16:19], v[94:97], v[118:121], v[16:19]
	v_mfma_f32_16x16x32_bf16 v[12:15], v[98:101], v[106:109], v[12:15]
	v_mfma_f32_16x16x32_bf16 v[8:11], v[98:101], v[110:113], v[8:11]
	v_mfma_f32_16x16x32_bf16 v[4:7], v[98:101], v[114:117], v[4:7]
	v_mfma_f32_16x16x32_bf16 v[0:3], v[98:101], v[118:121], v[0:3]
	v_mfma_f32_16x16x32_bf16 v[48:51], v[102:105], v[106:109], v[48:51]
	v_mfma_f32_16x16x32_bf16 v[52:55], v[102:105], v[110:113], v[52:55]
	v_mfma_f32_16x16x32_bf16 v[56:59], v[102:105], v[114:117], v[56:59]
	v_mfma_f32_16x16x32_bf16 v[60:63], v[102:105], v[118:121], v[60:63]
	s_waitcnt lgkmcnt(3)
	v_mfma_f32_16x16x32_bf16 v[44:47], v[122:125], v[138:141], v[44:47]
	s_waitcnt lgkmcnt(2)
	v_mfma_f32_16x16x32_bf16 v[40:43], v[122:125], v[142:145], v[40:43]
	s_waitcnt lgkmcnt(1)
	v_mfma_f32_16x16x32_bf16 v[36:39], v[122:125], v[150:153], v[36:39]
	s_waitcnt lgkmcnt(0)
	v_mfma_f32_16x16x32_bf16 v[32:35], v[122:125], v[154:157], v[32:35]
	v_mfma_f32_16x16x32_bf16 v[28:31], v[126:129], v[138:141], v[28:31]
	v_mfma_f32_16x16x32_bf16 v[24:27], v[126:129], v[142:145], v[24:27]
	v_mfma_f32_16x16x32_bf16 v[20:23], v[126:129], v[150:153], v[20:23]
	v_mfma_f32_16x16x32_bf16 v[16:19], v[126:129], v[154:157], v[16:19]
	v_mfma_f32_16x16x32_bf16 v[12:15], v[130:133], v[138:141], v[12:15]
	v_mfma_f32_16x16x32_bf16 v[8:11], v[130:133], v[142:145], v[8:11]
	v_mfma_f32_16x16x32_bf16 v[4:7], v[130:133], v[150:153], v[4:7]
	v_mfma_f32_16x16x32_bf16 v[0:3], v[130:133], v[154:157], v[0:3]
	v_mfma_f32_16x16x32_bf16 v[48:51], v[134:137], v[138:141], v[48:51]
	v_mfma_f32_16x16x32_bf16 v[52:55], v[134:137], v[142:145], v[52:55]
	v_mfma_f32_16x16x32_bf16 v[56:59], v[134:137], v[150:153], v[56:59]
	v_mfma_f32_16x16x32_bf16 v[60:63], v[134:137], v[154:157], v[60:63]
	s_cbranch_scc0 .LBB0_271

.LBB0_334:
	s_and_b32 s16, s84, 0x8000
	v_add_u32_e32 v89, s16, v87
	v_or_b32_e32 v126, s16, v88
	v_add_u32_e32 v102, v89, v85
	v_add_u32_e32 v118, v126, v85
	v_add_u32_e32 v89, v89, v86
	ds_read_b128 v[90:93], v102
	ds_read_b128 v[94:97], v102 offset:2048
	ds_read_b128 v[98:101], v102 offset:4096
	ds_read_b128 v[102:105], v102 offset:6144
	ds_read_b128 v[106:109], v118 offset:16384
	ds_read_b128 v[110:113], v118 offset:18432
	ds_read_b128 v[114:117], v118 offset:20480
	ds_read_b128 v[118:121], v118 offset:22528
	ds_read_b128 v[122:125], v89
	ds_read_b128 v[194:197], v89 offset:2048
	ds_read_b128 v[198:201], v89 offset:4096
	ds_read_b128 v[202:205], v89 offset:6144
	v_add_u32_e32 v89, v126, v86
	ds_read_b128 v[206:209], v89 offset:16384
	ds_read_b128 v[210:213], v89 offset:18432
	ds_read_b128 v[226:229], v89 offset:20480
	ds_read_b128 v[230:233], v89 offset:22528
	s_waitcnt lgkmcnt(11)
	v_mfma_f32_16x16x32_bf16 v[60:63], v[90:93], v[106:109], v[60:63]
	s_add_u32 s44, s44, 0x80
	s_addc_u32 s45, s45, 0
	s_add_i32 s15, s15, 1
	s_waitcnt lgkmcnt(10)
	v_mfma_f32_16x16x32_bf16 v[56:59], v[90:93], v[110:113], v[56:59]
	s_cmpk_lg_i32 s44, 0x400
	s_mov_b32 s84, s85
	s_waitcnt lgkmcnt(9)
	v_mfma_f32_16x16x32_bf16 v[52:55], v[90:93], v[114:117], v[52:55]
	s_waitcnt lgkmcnt(8)
	v_mfma_f32_16x16x32_bf16 v[48:51], v[90:93], v[118:121], v[48:51]
	v_mfma_f32_16x16x32_bf16 v[44:47], v[94:97], v[106:109], v[44:47]
	v_mfma_f32_16x16x32_bf16 v[40:43], v[94:97], v[110:113], v[40:43]
	v_mfma_f32_16x16x32_bf16 v[36:39], v[94:97], v[114:117], v[36:39]
	v_mfma_f32_16x16x32_bf16 v[32:35], v[94:97], v[118:121], v[32:35]
	v_mfma_f32_16x16x32_bf16 v[28:31], v[98:101], v[106:109], v[28:31]
	v_mfma_f32_16x16x32_bf16 v[24:27], v[98:101], v[110:113], v[24:27]
	v_mfma_f32_16x16x32_bf16 v[20:23], v[98:101], v[114:117], v[20:23]
	v_mfma_f32_16x16x32_bf16 v[16:19], v[98:101], v[118:121], v[16:19]
	v_mfma_f32_16x16x32_bf16 v[8:11], v[102:105], v[106:109], v[8:11]
	v_mfma_f32_16x16x32_bf16 v[0:3], v[102:105], v[110:113], v[0:3]
	v_mfma_f32_16x16x32_bf16 v[12:15], v[102:105], v[114:117], v[12:15]
	v_mfma_f32_16x16x32_bf16 v[4:7], v[102:105], v[118:121], v[4:7]
	s_waitcnt lgkmcnt(3)
	v_mfma_f32_16x16x32_bf16 v[60:63], v[122:125], v[206:209], v[60:63]
	s_waitcnt lgkmcnt(2)
	v_mfma_f32_16x16x32_bf16 v[56:59], v[122:125], v[210:213], v[56:59]
	s_waitcnt lgkmcnt(1)
	v_mfma_f32_16x16x32_bf16 v[52:55], v[122:125], v[226:229], v[52:55]
	s_waitcnt lgkmcnt(0)
	v_mfma_f32_16x16x32_bf16 v[48:51], v[122:125], v[230:233], v[48:51]
	v_mfma_f32_16x16x32_bf16 v[44:47], v[194:197], v[206:209], v[44:47]
	v_mfma_f32_16x16x32_bf16 v[40:43], v[194:197], v[210:213], v[40:43]
	v_mfma_f32_16x16x32_bf16 v[36:39], v[194:197], v[226:229], v[36:39]
	v_mfma_f32_16x16x32_bf16 v[32:35], v[194:197], v[230:233], v[32:35]
	v_mfma_f32_16x16x32_bf16 v[28:31], v[198:201], v[206:209], v[28:31]
	v_mfma_f32_16x16x32_bf16 v[24:27], v[198:201], v[210:213], v[24:27]
	v_mfma_f32_16x16x32_bf16 v[20:23], v[198:201], v[226:229], v[20:23]
	v_mfma_f32_16x16x32_bf16 v[16:19], v[198:201], v[230:233], v[16:19]
	v_mfma_f32_16x16x32_bf16 v[8:11], v[202:205], v[206:209], v[8:11]
	v_mfma_f32_16x16x32_bf16 v[0:3], v[202:205], v[210:213], v[0:3]
	v_mfma_f32_16x16x32_bf16 v[12:15], v[202:205], v[226:229], v[12:15]
	v_mfma_f32_16x16x32_bf16 v[4:7], v[202:205], v[230:233], v[4:7]
	s_cbranch_scc0 .LBB0_339

.LBB0_344:
	s_and_b32 s16, s84, 0x8000
	v_add_u32_e32 v89, s16, v86
	v_or_b32_e32 v126, s16, v87
	v_add_u32_e32 v102, v89, v84
	v_add_u32_e32 v118, v126, v84
	v_add_u32_e32 v89, v89, v85
	ds_read_b128 v[90:93], v102
	ds_read_b128 v[94:97], v102 offset:2048
	ds_read_b128 v[98:101], v102 offset:4096
	ds_read_b128 v[102:105], v102 offset:6144
	ds_read_b128 v[106:109], v118 offset:16384
	ds_read_b128 v[110:113], v118 offset:18432
	ds_read_b128 v[114:117], v118 offset:20480
	ds_read_b128 v[118:121], v118 offset:22528
	ds_read_b128 v[122:125], v89
	ds_read_b128 v[194:197], v89 offset:2048
	ds_read_b128 v[198:201], v89 offset:4096
	ds_read_b128 v[202:205], v89 offset:6144
	v_add_u32_e32 v89, v126, v85
	ds_read_b128 v[206:209], v89 offset:16384
	ds_read_b128 v[210:213], v89 offset:18432
	ds_read_b128 v[226:229], v89 offset:20480
	ds_read_b128 v[230:233], v89 offset:22528
	s_waitcnt lgkmcnt(11)
	v_mfma_f32_16x16x32_bf16 v[60:63], v[90:93], v[106:109], v[60:63]
	s_add_u32 s44, s44, 0x80
	s_addc_u32 s45, s45, 0
	s_add_i32 s15, s15, 1
	s_waitcnt lgkmcnt(10)
	v_mfma_f32_16x16x32_bf16 v[56:59], v[90:93], v[110:113], v[56:59]
	s_cmpk_lg_i32 s44, 0x400
	s_waitcnt lgkmcnt(9)
	v_mfma_f32_16x16x32_bf16 v[52:55], v[90:93], v[114:117], v[52:55]
	s_waitcnt lgkmcnt(8)
	v_mfma_f32_16x16x32_bf16 v[48:51], v[90:93], v[118:121], v[48:51]
	v_mfma_f32_16x16x32_bf16 v[44:47], v[94:97], v[106:109], v[44:47]
	v_mfma_f32_16x16x32_bf16 v[40:43], v[94:97], v[110:113], v[40:43]
	v_mfma_f32_16x16x32_bf16 v[36:39], v[94:97], v[114:117], v[36:39]
	v_mfma_f32_16x16x32_bf16 v[32:35], v[94:97], v[118:121], v[32:35]
	v_mfma_f32_16x16x32_bf16 v[28:31], v[98:101], v[106:109], v[28:31]
	v_mfma_f32_16x16x32_bf16 v[24:27], v[98:101], v[110:113], v[24:27]
	v_mfma_f32_16x16x32_bf16 v[20:23], v[98:101], v[114:117], v[20:23]
	v_mfma_f32_16x16x32_bf16 v[16:19], v[98:101], v[118:121], v[16:19]
	v_mfma_f32_16x16x32_bf16 v[8:11], v[102:105], v[106:109], v[8:11]
	v_mfma_f32_16x16x32_bf16 v[0:3], v[102:105], v[110:113], v[0:3]
	v_mfma_f32_16x16x32_bf16 v[12:15], v[102:105], v[114:117], v[12:15]
	v_mfma_f32_16x16x32_bf16 v[4:7], v[102:105], v[118:121], v[4:7]
	s_waitcnt lgkmcnt(3)
	v_mfma_f32_16x16x32_bf16 v[60:63], v[122:125], v[206:209], v[60:63]
	s_waitcnt lgkmcnt(2)
	v_mfma_f32_16x16x32_bf16 v[56:59], v[122:125], v[210:213], v[56:59]
	s_waitcnt lgkmcnt(1)
	v_mfma_f32_16x16x32_bf16 v[52:55], v[122:125], v[226:229], v[52:55]
	s_waitcnt lgkmcnt(0)
	v_mfma_f32_16x16x32_bf16 v[48:51], v[122:125], v[230:233], v[48:51]
	v_mfma_f32_16x16x32_bf16 v[44:47], v[194:197], v[206:209], v[44:47]
	v_mfma_f32_16x16x32_bf16 v[40:43], v[194:197], v[210:213], v[40:43]
	v_mfma_f32_16x16x32_bf16 v[36:39], v[194:197], v[226:229], v[36:39]
	v_mfma_f32_16x16x32_bf16 v[32:35], v[194:197], v[230:233], v[32:35]
	v_mfma_f32_16x16x32_bf16 v[28:31], v[198:201], v[206:209], v[28:31]
	v_mfma_f32_16x16x32_bf16 v[24:27], v[198:201], v[210:213], v[24:27]
	v_mfma_f32_16x16x32_bf16 v[20:23], v[198:201], v[226:229], v[20:23]
	v_mfma_f32_16x16x32_bf16 v[16:19], v[198:201], v[230:233], v[16:19]
	v_mfma_f32_16x16x32_bf16 v[8:11], v[202:205], v[206:209], v[8:11]
	v_mfma_f32_16x16x32_bf16 v[0:3], v[202:205], v[210:213], v[0:3]
	v_mfma_f32_16x16x32_bf16 v[12:15], v[202:205], v[226:229], v[12:15]
	v_mfma_f32_16x16x32_bf16 v[4:7], v[202:205], v[230:233], v[4:7]
	s_cbranch_scc0 .LBB0_346
	s_mov_b32 s84, s85
	s_branch .LBB0_340

.LBB0_347:
	s_and_b32 s14, s16, 0x8000
	v_add_u32_e32 v148, s14, v225
	v_or_b32_e32 v223, s14, v226
	v_add_u32_e32 v214, v148, v228
	ds_read_b128 v[230:233], v214
	ds_read_b128 v[234:237], v214 offset:2048
	ds_read_b128 v[238:241], v214 offset:4096
	ds_read_b128 v[242:245], v214 offset:6144
	v_add_u32_e32 v214, v223, v228
	ds_read_b128 v[246:249], v214 offset:16384
	ds_read_b128 v[250:253], v214 offset:18432
	ds_read_b128 v[218:221], v214 offset:20480
	ds_read_b128 v[214:217], v214 offset:22528
	s_waitcnt lgkmcnt(3)
	v_mfma_f32_16x16x32_bf16 v[124:127], v[230:233], v[246:249], v[124:127]
	s_waitcnt lgkmcnt(2)
	v_mfma_f32_16x16x32_bf16 v[120:123], v[230:233], v[250:253], v[120:123]
	s_waitcnt lgkmcnt(1)
	v_mfma_f32_16x16x32_bf16 v[116:119], v[230:233], v[218:221], v[116:119]
	s_waitcnt lgkmcnt(0)
	v_mfma_f32_16x16x32_bf16 v[112:115], v[230:233], v[214:217], v[112:115]
	v_mfma_f32_16x16x32_bf16 v[108:111], v[234:237], v[246:249], v[108:111]
	v_mfma_f32_16x16x32_bf16 v[104:107], v[234:237], v[250:253], v[104:107]
	v_mfma_f32_16x16x32_bf16 v[100:103], v[234:237], v[218:221], v[100:103]
	v_mfma_f32_16x16x32_bf16 v[96:99], v[234:237], v[214:217], v[96:99]
	v_mfma_f32_16x16x32_bf16 v[92:95], v[238:241], v[246:249], v[92:95]
	v_mfma_f32_16x16x32_bf16 v[88:91], v[238:241], v[250:253], v[88:91]
	v_mfma_f32_16x16x32_bf16 v[84:87], v[238:241], v[218:221], v[84:87]
	v_mfma_f32_16x16x32_bf16 v[80:83], v[238:241], v[214:217], v[80:83]
	v_mfma_f32_16x16x32_bf16 v[76:79], v[242:245], v[246:249], v[76:79]
	v_mfma_f32_16x16x32_bf16 v[72:75], v[242:245], v[250:253], v[72:75]
	v_mfma_f32_16x16x32_bf16 v[68:71], v[242:245], v[218:221], v[68:71]
	v_mfma_f32_16x16x32_bf16 v[64:67], v[242:245], v[214:217], v[64:67]
	v_add_u32_e32 v148, v148, v229
	ds_read_b128 v[214:217], v148
	ds_read_b128 v[218:221], v148 offset:2048
	ds_read_b128 v[230:233], v148 offset:4096
	ds_read_b128 v[234:237], v148 offset:6144
	v_add_u32_e32 v148, v223, v229
	ds_read_b128 v[238:241], v148 offset:16384
	ds_read_b128 v[242:245], v148 offset:18432
	ds_read_b128 v[246:249], v148 offset:20480
	ds_read_b128 v[250:253], v148 offset:22528
	s_waitcnt lgkmcnt(3)
	v_mfma_f32_16x16x32_bf16 v[124:127], v[214:217], v[238:241], v[124:127]
	s_waitcnt lgkmcnt(2)
	v_mfma_f32_16x16x32_bf16 v[120:123], v[214:217], v[242:245], v[120:123]
	s_waitcnt lgkmcnt(1)
	v_mfma_f32_16x16x32_bf16 v[116:119], v[214:217], v[246:249], v[116:119]
	s_waitcnt lgkmcnt(0)
	v_mfma_f32_16x16x32_bf16 v[112:115], v[214:217], v[250:253], v[112:115]
	v_mfma_f32_16x16x32_bf16 v[108:111], v[218:221], v[238:241], v[108:111]
	v_mfma_f32_16x16x32_bf16 v[104:107], v[218:221], v[242:245], v[104:107]
	v_mfma_f32_16x16x32_bf16 v[100:103], v[218:221], v[246:249], v[100:103]
	v_mfma_f32_16x16x32_bf16 v[96:99], v[218:221], v[250:253], v[96:99]
	v_mfma_f32_16x16x32_bf16 v[92:95], v[230:233], v[238:241], v[92:95]
	v_mfma_f32_16x16x32_bf16 v[88:91], v[230:233], v[242:245], v[88:91]
	v_mfma_f32_16x16x32_bf16 v[84:87], v[230:233], v[246:249], v[84:87]
	v_mfma_f32_16x16x32_bf16 v[80:83], v[230:233], v[250:253], v[80:83]
	v_mfma_f32_16x16x32_bf16 v[76:79], v[234:237], v[238:241], v[76:79]
	v_mfma_f32_16x16x32_bf16 v[72:75], v[234:237], v[242:245], v[72:75]
	v_mfma_f32_16x16x32_bf16 v[68:71], v[234:237], v[246:249], v[68:71]
	v_mfma_f32_16x16x32_bf16 v[64:67], v[234:237], v[250:253], v[64:67]
	s_add_i32 s16, s16, 0x8000
	s_add_u32 s44, s44, 0x80
	s_addc_u32 s45, s45, 0
	s_cmpk_lg_i32 s44, 0x400
	s_cbranch_scc0 .LBB0_328

.LBB0_545:
	s_and_b32 s14, s16, 0x8000
	v_add_u32_e32 v122, s14, v88
	v_or_b32_e32 v138, s14, v89
	v_add_u32_e32 v102, v122, v86
	v_add_u32_e32 v118, v138, v86
	v_add_u32_e32 v134, v122, v87
	v_add_u32_e32 v146, v138, v87
	ds_read_b128 v[90:93], v102
	ds_read_b128 v[94:97], v102 offset:2048
	ds_read_b128 v[98:101], v102 offset:4096
	ds_read_b128 v[102:105], v102 offset:6144
	ds_read_b128 v[106:109], v118 offset:16384
	ds_read_b128 v[110:113], v118 offset:18432
	ds_read_b128 v[114:117], v118 offset:20480
	ds_read_b128 v[118:121], v118 offset:22528
	ds_read_b128 v[122:125], v134
	ds_read_b128 v[126:129], v134 offset:2048
	ds_read_b128 v[130:133], v134 offset:4096
	ds_read_b128 v[134:137], v134 offset:6144
	ds_read_b128 v[138:141], v146 offset:16384
	ds_read_b128 v[142:145], v146 offset:18432
	ds_read_b128 v[150:153], v146 offset:20480
	ds_read_b128 v[154:157], v146 offset:22528
	s_waitcnt lgkmcnt(11)
	v_mfma_f32_16x16x32_bf16 v[60:63], v[90:93], v[106:109], v[60:63]
	s_add_i32 s16, s16, 0x8000
	s_add_u32 s8, s8, 0x80
	s_addc_u32 s9, s9, 0
	s_waitcnt lgkmcnt(10)
	v_mfma_f32_16x16x32_bf16 v[56:59], v[90:93], v[110:113], v[56:59]
	s_add_i32 s17, s17, 1
	s_cmpk_lg_i32 s8, 0x800
	s_waitcnt lgkmcnt(9)
	v_mfma_f32_16x16x32_bf16 v[52:55], v[90:93], v[114:117], v[52:55]
	s_waitcnt lgkmcnt(8)
	v_mfma_f32_16x16x32_bf16 v[48:51], v[90:93], v[118:121], v[48:51]
	v_mfma_f32_16x16x32_bf16 v[44:47], v[94:97], v[106:109], v[44:47]
	v_mfma_f32_16x16x32_bf16 v[40:43], v[94:97], v[110:113], v[40:43]
	v_mfma_f32_16x16x32_bf16 v[36:39], v[94:97], v[114:117], v[36:39]
	v_mfma_f32_16x16x32_bf16 v[32:35], v[94:97], v[118:121], v[32:35]
	v_mfma_f32_16x16x32_bf16 v[28:31], v[98:101], v[106:109], v[28:31]
	v_mfma_f32_16x16x32_bf16 v[20:23], v[98:101], v[110:113], v[20:23]
	v_mfma_f32_16x16x32_bf16 v[12:15], v[98:101], v[114:117], v[12:15]
	v_mfma_f32_16x16x32_bf16 v[8:11], v[98:101], v[118:121], v[8:11]
	v_mfma_f32_16x16x32_bf16 v[4:7], v[102:105], v[106:109], v[4:7]
	v_mfma_f32_16x16x32_bf16 v[0:3], v[102:105], v[110:113], v[0:3]
	v_mfma_f32_16x16x32_bf16 v[24:27], v[102:105], v[114:117], v[24:27]
	v_mfma_f32_16x16x32_bf16 v[16:19], v[102:105], v[118:121], v[16:19]
	s_waitcnt lgkmcnt(3)
	v_mfma_f32_16x16x32_bf16 v[60:63], v[122:125], v[138:141], v[60:63]
	s_waitcnt lgkmcnt(2)
	v_mfma_f32_16x16x32_bf16 v[56:59], v[122:125], v[142:145], v[56:59]
	s_waitcnt lgkmcnt(1)
	v_mfma_f32_16x16x32_bf16 v[52:55], v[122:125], v[150:153], v[52:55]
	s_waitcnt lgkmcnt(0)
	v_mfma_f32_16x16x32_bf16 v[48:51], v[122:125], v[154:157], v[48:51]
	v_mfma_f32_16x16x32_bf16 v[44:47], v[126:129], v[138:141], v[44:47]
	v_mfma_f32_16x16x32_bf16 v[40:43], v[126:129], v[142:145], v[40:43]
	v_mfma_f32_16x16x32_bf16 v[36:39], v[126:129], v[150:153], v[36:39]
	v_mfma_f32_16x16x32_bf16 v[32:35], v[126:129], v[154:157], v[32:35]
	v_mfma_f32_16x16x32_bf16 v[28:31], v[130:133], v[138:141], v[28:31]
	v_mfma_f32_16x16x32_bf16 v[20:23], v[130:133], v[142:145], v[20:23]
	v_mfma_f32_16x16x32_bf16 v[12:15], v[130:133], v[150:153], v[12:15]
	v_mfma_f32_16x16x32_bf16 v[8:11], v[130:133], v[154:157], v[8:11]
	v_mfma_f32_16x16x32_bf16 v[4:7], v[134:137], v[138:141], v[4:7]
	v_mfma_f32_16x16x32_bf16 v[0:3], v[134:137], v[142:145], v[0:3]
	v_mfma_f32_16x16x32_bf16 v[24:27], v[134:137], v[150:153], v[24:27]
	v_mfma_f32_16x16x32_bf16 v[16:19], v[134:137], v[154:157], v[16:19]
	s_cbranch_scc0 .LBB0_552
